# v107 + nt hint on G3 last-use streaming loads (decay tile, q/k, v, gate rows) so the G2 states stay cached for later G3 units
# speedup vs baseline: 1.0034x; 1.0034x over previous
.LBB0_759:
	s_lshl_b32 s28, s20, 4
	s_lshl_b32 s29, s36, 2
	s_or_b32 s28, s29, s28
	s_add_i32 s72, s28, s37
	s_ashr_i32 s73, s72, 31
	s_lshl_b64 s[28:29], s[72:73], 15
	v_lshl_add_u64 v[32:33], v[88:89], 0, s[28:29]
	v_lshl_add_u64 v[34:35], v[104:105], 2, v[32:33]
	v_lshl_add_u64 v[36:37], v[106:107], 2, v[32:33]
	global_load_dwordx4 v[68:71], v[34:35], off nt
	global_load_dwordx4 v[64:67], v[36:37], off nt
	v_lshl_add_u64 v[34:35], v[108:109], 2, v[32:33]
	v_lshl_add_u64 v[32:33], v[110:111], 2, v[32:33]
	global_load_dwordx4 v[76:79], v[34:35], off nt
	global_load_dwordx4 v[72:75], v[32:33], off nt
	s_cmp_eq_u32 s20, 0
	s_cselect_b64 s[64:65], -1, 0
	s_cmp_lg_u32 s20, 0
	s_cselect_b64 s[70:71], -1, 0
	s_lshl_b32 s28, s36, 13
	s_lshl_b32 s20, s20, 6
	s_add_i32 s20, s20, s28
	s_sub_i32 s36, s20, 64
	v_add_u32_e32 v36, s36, v159
	s_lshl_b32 s20, s37, 8
	v_cndmask_b32_e64 v142, v36, v103, s[64:65]
	v_lshl_add_u64 v[32:33], v[90:91], 0, s[20:21]
	v_lshl_add_u64 v[34:35], v[92:93], 0, s[20:21]
	v_cmp_lt_i32_e32 vcc, -1, v142
	v_mov_b32_e32 v40, 0
	v_mov_b32_e32 v84, 0
	v_mov_b32_e32 v85, 0
	v_mov_b32_e32 v86, 0
	v_mov_b32_e32 v87, 0
	v_mov_b32_e32 v80, 0
	v_mov_b32_e32 v81, 0
	v_mov_b32_e32 v82, 0
	v_mov_b32_e32 v83, 0
	s_and_saveexec_b64 s[56:57], vcc
	s_cbranch_execz .LBB0_761
	v_lshlrev_b64 v[38:39], 10, v[142:143]
	v_lshl_add_u64 v[42:43], v[34:35], 0, v[38:39]
	v_lshl_add_u64 v[38:39], v[32:33], 0, v[38:39]
	global_load_dwordx4 v[84:87], v[38:39], off nt
	global_load_dwordx4 v[80:83], v[42:43], off nt
.LBB0_761:
	s_or_b64 exec, exec, s[56:57]
	v_add_u32_e32 v36, 32, v36
	v_cndmask_b32_e64 v142, v36, v163, s[64:65]
	v_cmp_lt_i32_e32 vcc, -1, v142
	v_mov_b32_e32 v60, 0
	v_mov_b32_e32 v61, 0
	v_mov_b32_e32 v62, 0
	v_mov_b32_e32 v63, 0
	v_mov_b32_e32 v56, 0
	v_mov_b32_e32 v57, 0
	v_mov_b32_e32 v58, 0
	v_mov_b32_e32 v59, 0
	s_and_saveexec_b64 s[56:57], vcc
	s_cbranch_execz .LBB0_763
	v_lshlrev_b64 v[36:37], 10, v[142:143]
	v_lshl_add_u64 v[32:33], v[32:33], 0, v[36:37]
	v_lshl_add_u64 v[34:35], v[34:35], 0, v[36:37]
	global_load_dwordx4 v[60:63], v[32:33], off nt
	global_load_dwordx4 v[56:59], v[34:35], off nt
.LBB0_763:
	s_or_b64 exec, exec, s[56:57]
	v_add_u32_e32 v32, s36, v164
	s_lshl_b32 s28, s37, 9
	s_mov_b32 s29, s21
	v_cndmask_b32_e64 v124, v32, v165, s[64:65]
	v_lshl_add_u64 v[116:117], v[94:95], 0, s[28:29]
	v_cmp_lt_i32_e64 s[62:63], -1, v124
	v_mov_b32_e32 v41, 0
	v_mov_b32_e32 v42, 0
	v_mov_b32_e32 v43, 0
	s_and_saveexec_b64 s[56:57], s[62:63]
	s_cbranch_execz .LBB0_765
	v_mov_b32_e32 v125, v143
	v_lshlrev_b64 v[32:33], 11, v[124:125]
	v_lshl_add_u64 v[32:33], v[116:117], 0, v[32:33]
	global_load_dwordx4 v[40:43], v[32:33], off nt
.LBB0_765:
	s_or_b64 exec, exec, s[56:57]
	v_add_u32_e32 v32, s36, v166
	v_cndmask_b32_e64 v122, v32, v167, s[64:65]
	v_cmp_lt_i32_e64 s[60:61], -1, v122
	v_mov_b32_e32 v44, 0
	v_mov_b32_e32 v48, 0
	v_mov_b32_e32 v49, 0
	v_mov_b32_e32 v50, 0
	v_mov_b32_e32 v51, 0
	s_and_saveexec_b64 s[56:57], s[60:61]
	s_cbranch_execz .LBB0_767
	v_mov_b32_e32 v123, v143
	v_lshlrev_b64 v[32:33], 11, v[122:123]
	v_lshl_add_u64 v[32:33], v[116:117], 0, v[32:33]
	global_load_dwordx4 v[48:51], v[32:33], off nt
.LBB0_767:
	s_or_b64 exec, exec, s[56:57]
	v_add_u32_e32 v32, s36, v168
	v_cndmask_b32_e64 v120, v32, v169, s[64:65]
	v_cmp_lt_i32_e64 s[58:59], -1, v120
	v_mov_b32_e32 v45, 0
	v_mov_b32_e32 v46, 0
	v_mov_b32_e32 v47, 0
	s_and_saveexec_b64 s[56:57], s[58:59]
	s_cbranch_execz .LBB0_769
	v_mov_b32_e32 v121, v143
	v_lshlrev_b64 v[32:33], 11, v[120:121]
	v_lshl_add_u64 v[32:33], v[116:117], 0, v[32:33]
	global_load_dwordx4 v[44:47], v[32:33], off nt
.LBB0_769:
	s_or_b64 exec, exec, s[56:57]
	v_add_u32_e32 v32, s36, v170
	v_cndmask_b32_e64 v118, v32, v171, s[64:65]
	v_cmp_lt_i32_e64 s[56:57], -1, v118
	v_mov_b32_e32 v52, 0
	v_mov_b32_e32 v53, 0
	v_mov_b32_e32 v54, 0
	v_mov_b32_e32 v55, 0
	s_and_saveexec_b64 s[74:75], s[56:57]
	s_cbranch_execz .LBB0_771
	v_mov_b32_e32 v119, v143
	v_lshlrev_b64 v[32:33], 11, v[118:119]
	v_lshl_add_u64 v[32:33], v[116:117], 0, v[32:33]
	global_load_dwordx4 v[52:55], v[32:33], off nt

.LBB0_773:
	s_nop 0
	global_load_dwordx4 v[36:39], v[98:99], off
	global_load_dwordx4 v[32:35], v[98:99], off offset:64
	v_or_b32_e32 v119, s36, v158
	s_lshl_b32 s20, s20, 1
	v_cndmask_b32_e64 v142, v119, -1, s[64:65]
	v_lshl_add_u64 v[126:127], v[100:101], 0, s[20:21]
	v_lshlrev_b64 v[128:129], 11, v[142:143]
	v_cmp_lt_i32_e32 vcc, -1, v142
	v_lshl_add_u64 v[128:129], v[126:127], 0, v[128:129]
	v_mov_b32_e32 v138, 0
	v_mov_b32_e32 v140, 0
	v_mov_b32_e32 v141, 0
	s_and_saveexec_b64 s[72:73], vcc
	s_cbranch_execz .LBB0_775
	global_load_dwordx2 v[140:141], v[128:129], off nt
.LBB0_775:
	s_or_b64 exec, exec, s[72:73]
	v_mov_b32_e32 v139, 0
	s_and_saveexec_b64 s[72:73], vcc
	s_cbranch_execz .LBB0_777
	global_load_dwordx2 v[138:139], v[128:129], off offset:32 nt
.LBB0_777:
	s_or_b64 exec, exec, s[72:73]
	v_or_b32_e32 v119, s36, v172
	v_cndmask_b32_e64 v142, v119, -1, s[64:65]
	v_lshlrev_b64 v[128:129], 11, v[142:143]
	v_cmp_lt_i32_e32 vcc, -1, v142
	v_lshl_add_u64 v[128:129], v[126:127], 0, v[128:129]
	v_mov_b32_e32 v134, 0
	v_mov_b32_e32 v136, 0
	v_mov_b32_e32 v137, 0
	s_and_saveexec_b64 s[72:73], vcc
	s_cbranch_execz .LBB0_779
	global_load_dwordx2 v[136:137], v[128:129], off nt
.LBB0_779:
	s_or_b64 exec, exec, s[72:73]
	v_mov_b32_e32 v135, 0
	s_and_saveexec_b64 s[72:73], vcc
	s_cbranch_execz .LBB0_781
	global_load_dwordx2 v[134:135], v[128:129], off offset:32 nt
.LBB0_781:
	s_or_b64 exec, exec, s[72:73]
	v_or_b32_e32 v119, s36, v173
	v_cndmask_b32_e64 v142, v119, -1, s[64:65]
	v_lshlrev_b64 v[128:129], 11, v[142:143]
	v_cmp_lt_i32_e32 vcc, -1, v142
	v_lshl_add_u64 v[128:129], v[126:127], 0, v[128:129]
	v_mov_b32_e32 v130, 0
	v_mov_b32_e32 v132, 0
	v_mov_b32_e32 v133, 0
	s_and_saveexec_b64 s[72:73], vcc
	s_cbranch_execz .LBB0_783
	global_load_dwordx2 v[132:133], v[128:129], off nt
.LBB0_783:
	s_or_b64 exec, exec, s[72:73]
	v_mov_b32_e32 v131, 0
	s_and_saveexec_b64 s[72:73], vcc
	s_cbranch_execz .LBB0_785
	global_load_dwordx2 v[130:131], v[128:129], off offset:32 nt
.LBB0_785:
	s_or_b64 exec, exec, s[72:73]
	v_or_b32_e32 v119, s36, v174
	v_cndmask_b32_e64 v142, v119, v175, s[64:65]
	v_lshlrev_b64 v[128:129], 11, v[142:143]
	v_cmp_lt_i32_e32 vcc, -1, v142
	v_lshl_add_u64 v[156:157], v[126:127], 0, v[128:129]
	v_mov_b32_e32 v126, 0
	v_mov_b32_e32 v128, 0
	v_mov_b32_e32 v129, 0
	s_and_saveexec_b64 s[64:65], vcc
	s_cbranch_execz .LBB0_787
	global_load_dwordx2 v[128:129], v[156:157], off nt
.LBB0_787:
	s_or_b64 exec, exec, s[64:65]
	v_mov_b32_e32 v127, 0
	s_and_saveexec_b64 s[64:65], vcc
	s_cbranch_execz .LBB0_789
	global_load_dwordx2 v[126:127], v[156:157], off offset:32 nt
